# hot loop heads (7 GEMM K-loops, FoX loop, attn0 step loop) aligned to 64 bytes
# baseline (speedup 1.0000x reference)
.LBB0_175:
	s_waitcnt vmcnt(0) lgkmcnt(0)
	s_mov_b64 s[38:39], 0
	.p2align	6

.LBB0_180:
	s_cmp_gt_i32 s47, s46
	s_cbranch_scc1 .LBB0_188
	s_cmp_lg_u32 s46, s47
	s_cbranch_scc1 .Lfx_body
	v_add_u32_e32 v1, s48, v189
	ds_read_b128 v[126:129], v1 offset:32768
	ds_read_b128 v[106:109], v1 offset:40960
	ds_read_b128 v[98:101], v1 offset:33792
	ds_read_b128 v[102:105], v1 offset:41984
	ds_read_b128 v[86:89], v1 offset:34816
	ds_read_b128 v[94:97], v1 offset:43008
	ds_read_b128 v[82:85], v1 offset:35840
	ds_read_b128 v[90:93], v1 offset:44032
	ds_read_b128 v[34:37], v175
	ds_read_b128 v[38:41], v175 offset:16
	ds_read_b128 v[42:45], v175 offset:64
	ds_read_b128 v[46:49], v175 offset:80
	ds_read_b128 v[50:53], v175 offset:128
	ds_read_b128 v[54:57], v175 offset:144
	ds_read_b128 v[58:61], v175 offset:192
	ds_read_b128 v[62:65], v175 offset:208
	s_waitcnt lgkmcnt(0)
	v_mfma_f32_32x32x16_bf16 v[34:49], v[126:129], v[66:69], v[34:49]
	v_mfma_f32_32x32x16_bf16 v[50:65], v[106:109], v[66:69], v[50:65]
	v_mfma_f32_32x32x16_bf16 v[34:49], v[98:101], v[70:73], v[34:49]
	v_mfma_f32_32x32x16_bf16 v[50:65], v[102:105], v[70:73], v[50:65]
	v_mfma_f32_32x32x16_bf16 v[34:49], v[86:89], v[74:77], v[34:49]
	v_mfma_f32_32x32x16_bf16 v[50:65], v[94:97], v[74:77], v[50:65]
	v_mfma_f32_32x32x16_bf16 v[34:49], v[82:85], v[78:81], v[34:49]
	v_mfma_f32_32x32x16_bf16 v[50:65], v[90:93], v[78:81], v[50:65]
	s_nop 1
	v_add_u32_e32 v1, s50, v166
	v_add_u32_e32 v163, 0xe0, v1
	v_add_u32_e32 v162, 0xc0, v1
	v_cmp_le_i32_e32 vcc, v163, v186
	s_nop 6
	v_cndmask_b32_e32 v50, v239, v50, vcc
	v_cmp_lt_i32_e32 vcc, v162, v186
	s_nop 1
	v_cndmask_b32_e32 v35, v239, v35, vcc
	v_cmp_le_i32_e32 vcc, v162, v186
	v_add_u32_e32 v162, 0xe1, v1
	s_nop 0
	v_cndmask_b32_e32 v34, v239, v34, vcc
	v_cmp_le_i32_e32 vcc, v162, v186
	v_add_u32_e32 v162, 0xc2, v1
	s_nop 0
	v_cndmask_b32_e32 v51, v239, v51, vcc
	v_cmp_le_i32_e32 vcc, v162, v186
	v_add_u32_e32 v162, 0xe2, v1
	s_nop 0
	v_cndmask_b32_e32 v36, v239, v36, vcc
	v_cmp_le_i32_e32 vcc, v162, v186
	v_add_u32_e32 v162, 0xc3, v1
	s_nop 0
	v_cndmask_b32_e32 v52, v239, v52, vcc
	v_cmp_le_i32_e32 vcc, v162, v186
	v_add_u32_e32 v162, 0xe3, v1
	s_nop 0
	v_cndmask_b32_e32 v37, v239, v37, vcc
	v_cmp_le_i32_e32 vcc, v162, v186
	v_add_u32_e32 v162, 0xc4, v1
	s_nop 0
	v_cndmask_b32_e32 v53, v239, v53, vcc
	v_cmp_le_i32_e32 vcc, v162, v186
	v_add_u32_e32 v162, 0xe4, v1
	s_nop 0
	v_cndmask_b32_e32 v38, v239, v38, vcc
	v_cmp_le_i32_e32 vcc, v162, v186
	v_add_u32_e32 v162, 0xc5, v1
	s_nop 0
	v_cndmask_b32_e32 v54, v239, v54, vcc
	v_cmp_le_i32_e32 vcc, v162, v186
	v_add_u32_e32 v162, 0xe5, v1
	s_nop 0
	v_cndmask_b32_e32 v39, v239, v39, vcc
	v_cmp_le_i32_e32 vcc, v162, v186
	v_add_u32_e32 v162, 0xc6, v1
	s_nop 0
	v_cndmask_b32_e32 v55, v239, v55, vcc
	v_cmp_le_i32_e32 vcc, v162, v186
	v_add_u32_e32 v162, 0xe6, v1
	s_nop 0
	v_cndmask_b32_e32 v40, v239, v40, vcc
	v_cmp_le_i32_e32 vcc, v162, v186
	v_add_u32_e32 v162, 0xc7, v1
	s_nop 0
	v_cndmask_b32_e32 v56, v239, v56, vcc
	v_cmp_le_i32_e32 vcc, v162, v186
	v_add_u32_e32 v162, 0xe7, v1
	s_nop 0
	v_cndmask_b32_e32 v41, v239, v41, vcc
	v_cmp_le_i32_e32 vcc, v162, v186
	v_add_u32_e32 v162, 0xd0, v1
	s_nop 0
	v_cndmask_b32_e32 v57, v239, v57, vcc
	v_cmp_le_i32_e32 vcc, v162, v186
	v_add_u32_e32 v162, 0xf0, v1
	s_nop 0
	v_cndmask_b32_e32 v42, v239, v42, vcc
	v_cmp_le_i32_e32 vcc, v162, v186
	v_add_u32_e32 v162, 0xd1, v1
	s_nop 0
	v_cndmask_b32_e32 v58, v239, v58, vcc
	v_cmp_le_i32_e32 vcc, v162, v186
	v_add_u32_e32 v162, 0xf1, v1
	s_nop 0
	v_cndmask_b32_e32 v43, v239, v43, vcc
	v_cmp_le_i32_e32 vcc, v162, v186
	v_add_u32_e32 v162, 0xd2, v1
	s_nop 0
	v_cndmask_b32_e32 v59, v239, v59, vcc
	v_cmp_le_i32_e32 vcc, v162, v186
	v_add_u32_e32 v162, 0xf2, v1
	s_nop 0
	v_cndmask_b32_e32 v44, v239, v44, vcc
	v_cmp_le_i32_e32 vcc, v162, v186
	v_add_u32_e32 v162, 0xd3, v1
	s_nop 0
	v_cndmask_b32_e32 v60, v239, v60, vcc
	v_cmp_le_i32_e32 vcc, v162, v186
	v_add_u32_e32 v162, 0xf3, v1
	s_nop 0
	v_cndmask_b32_e32 v45, v239, v45, vcc
	v_cmp_le_i32_e32 vcc, v162, v186
	v_add_u32_e32 v162, 0xd4, v1
	s_nop 0
	v_cndmask_b32_e32 v61, v239, v61, vcc
	v_cmp_le_i32_e32 vcc, v162, v186
	v_add_u32_e32 v162, 0xf4, v1
	s_nop 0
	v_cndmask_b32_e32 v46, v239, v46, vcc
	v_cmp_le_i32_e32 vcc, v162, v186
	v_add_u32_e32 v162, 0xd5, v1
	s_nop 0
	v_cndmask_b32_e32 v62, v239, v62, vcc
	v_cmp_le_i32_e32 vcc, v162, v186
	v_add_u32_e32 v162, 0xf5, v1
	s_nop 0
	v_cndmask_b32_e32 v47, v239, v47, vcc
	v_cmp_le_i32_e32 vcc, v162, v186
	v_add_u32_e32 v162, 0xd6, v1
	s_nop 0
	v_cndmask_b32_e32 v63, v239, v63, vcc
	v_cmp_le_i32_e32 vcc, v162, v186
	v_add_u32_e32 v162, 0xf6, v1
	s_nop 0
	v_cndmask_b32_e32 v48, v239, v48, vcc
	v_cmp_le_i32_e32 vcc, v162, v186
	v_add_u32_e32 v162, 0xd7, v1
	v_add_u32_e32 v1, 0xf7, v1
	v_cndmask_b32_e32 v64, v239, v64, vcc
	v_cmp_le_i32_e32 vcc, v162, v186
	s_nop 1
	v_cndmask_b32_e32 v49, v239, v49, vcc
	v_cmp_le_i32_e32 vcc, v1, v186
	s_nop 1
	v_cndmask_b32_e32 v65, v239, v65, vcc
	v_mov_b32_e32 v163, v0
	v_max3_f32 v1, v34, v35, v36
	v_max3_f32 v208, v50, v51, v52
	v_max3_f32 v1, v1, v37, v38
	v_max3_f32 v1, v1, v39, v40
	v_max3_f32 v1, v1, v41, v42
	v_max3_f32 v1, v1, v43, v44
	v_max3_f32 v1, v1, v45, v46
	v_max3_f32 v1, v1, v47, v48
	v_max3_f32 v208, v208, v53, v54
	v_max3_f32 v208, v208, v55, v56
	v_max3_f32 v208, v208, v57, v58
	v_max3_f32 v208, v208, v59, v60
	v_max3_f32 v208, v208, v61, v62
	v_max3_f32 v208, v208, v63, v64
	v_max3_f32 v208, v208, v65, v49
	v_max_f32_e32 v1, v1, v208
	ds_bpermute_b32 v209, v203, v1
	s_waitcnt lgkmcnt(0)
	v_max_f32_e32 v1, v1, v209
	v_cvt_pk_bf16_f32 v209, v1, v1
	v_lshlrev_b32_e32 v200, 16, v209
	v_xor_b32_e32 v209, 0x8000, v209
	v_and_b32_e32 v209, 0xffff, v209
	v_cndmask_b32_e64 v162, 0, v209, s[16:17]
	v_sub_f32_e32 v34, v34, v200
	v_sub_f32_e32 v35, v35, v200
	v_sub_f32_e32 v36, v36, v200
	v_sub_f32_e32 v37, v37, v200
	v_sub_f32_e32 v38, v38, v200
	v_sub_f32_e32 v39, v39, v200
	v_sub_f32_e32 v40, v40, v200
	v_sub_f32_e32 v41, v41, v200
	v_sub_f32_e32 v42, v42, v200
	v_sub_f32_e32 v43, v43, v200
	v_sub_f32_e32 v44, v44, v200
	v_sub_f32_e32 v45, v45, v200
	v_sub_f32_e32 v46, v46, v200
	v_sub_f32_e32 v47, v47, v200
	v_sub_f32_e32 v48, v48, v200
	v_sub_f32_e32 v49, v49, v200
	v_sub_f32_e32 v50, v50, v200
	v_sub_f32_e32 v51, v51, v200
	v_sub_f32_e32 v52, v52, v200
	v_sub_f32_e32 v53, v53, v200
	v_sub_f32_e32 v54, v54, v200
	v_sub_f32_e32 v55, v55, v200
	v_sub_f32_e32 v56, v56, v200
	v_sub_f32_e32 v57, v57, v200
	v_sub_f32_e32 v58, v58, v200
	v_sub_f32_e32 v59, v59, v200
	v_sub_f32_e32 v60, v60, v200
	v_sub_f32_e32 v61, v61, v200
	v_sub_f32_e32 v62, v62, v200
	v_sub_f32_e32 v63, v63, v200
	v_sub_f32_e32 v64, v64, v200
	v_sub_f32_e32 v65, v65, v200
	.p2align	6

.LBB0_218:
	s_lshl_b32 s16, s42, 8
	s_ashr_i32 s17, s16, 31
	s_lshl_b64 s[16:17], s[16:17], 11
	s_add_u32 s16, s80, s16
	s_addc_u32 s17, s81, s17
	s_and_b64 s[22:23], s[2:3], exec
	s_cselect_b32 s44, s17, s27
	s_cselect_b32 s45, s16, s26
	s_lshl_b32 s22, s41, 8
	s_ashr_i32 s23, s22, 31
	s_lshl_b64 s[22:23], s[22:23], 11
	s_add_u32 s22, s29, s22
	s_addc_u32 s23, s30, s23
	s_and_b64 s[24:25], s[2:3], exec
	s_cselect_b32 s46, s23, s5
	s_cselect_b32 s47, s22, s4
	s_add_u32 s48, s4, 0x100
	s_addc_u32 s49, s5, 0
	s_add_u32 s4, s26, 0x40080
	v_mov_b32_e32 v2, 0
	s_addc_u32 s5, s27, 0
	s_mov_b32 s50, -2
	v_mov_b32_e32 v3, v2
	v_mov_b32_e32 v4, v2
	v_mov_b32_e32 v5, v2
	v_mov_b32_e32 v6, v2
	v_mov_b32_e32 v7, v2
	v_mov_b32_e32 v8, v2
	v_mov_b32_e32 v9, v2
	v_mov_b32_e32 v18, v2
	v_mov_b32_e32 v19, v2
	v_mov_b32_e32 v20, v2
	v_mov_b32_e32 v21, v2
	v_mov_b32_e32 v22, v2
	v_mov_b32_e32 v23, v2
	v_mov_b32_e32 v24, v2
	v_mov_b32_e32 v25, v2
	v_mov_b32_e32 v34, v2
	v_mov_b32_e32 v35, v2
	v_mov_b32_e32 v36, v2
	v_mov_b32_e32 v37, v2
	v_mov_b32_e32 v38, v2
	v_mov_b32_e32 v39, v2
	v_mov_b32_e32 v40, v2
	v_mov_b32_e32 v41, v2
	v_mov_b32_e32 v50, v2
	v_mov_b32_e32 v51, v2
	v_mov_b32_e32 v52, v2
	v_mov_b32_e32 v53, v2
	v_mov_b32_e32 v54, v2
	v_mov_b32_e32 v55, v2
	v_mov_b32_e32 v56, v2
	v_mov_b32_e32 v57, v2
	v_mov_b32_e32 v10, v2
	v_mov_b32_e32 v11, v2
	v_mov_b32_e32 v12, v2
	v_mov_b32_e32 v13, v2
	v_mov_b32_e32 v14, v2
	v_mov_b32_e32 v15, v2
	v_mov_b32_e32 v16, v2
	v_mov_b32_e32 v17, v2
	v_mov_b32_e32 v26, v2
	v_mov_b32_e32 v27, v2
	v_mov_b32_e32 v28, v2
	v_mov_b32_e32 v29, v2
	v_mov_b32_e32 v30, v2
	v_mov_b32_e32 v31, v2
	v_mov_b32_e32 v32, v2
	v_mov_b32_e32 v33, v2
	v_mov_b32_e32 v42, v2
	v_mov_b32_e32 v43, v2
	v_mov_b32_e32 v44, v2
	v_mov_b32_e32 v45, v2
	v_mov_b32_e32 v46, v2
	v_mov_b32_e32 v47, v2
	v_mov_b32_e32 v48, v2
	v_mov_b32_e32 v49, v2
	v_mov_b32_e32 v58, v2
	v_mov_b32_e32 v59, v2
	v_mov_b32_e32 v60, v2
	v_mov_b32_e32 v61, v2
	v_mov_b32_e32 v62, v2
	v_mov_b32_e32 v63, v2
	v_mov_b32_e32 v64, v2
	v_mov_b32_e32 v65, v2
	v_mov_b32_e32 v66, v2
	v_mov_b32_e32 v67, v2
	v_mov_b32_e32 v68, v2
	v_mov_b32_e32 v69, v2
	v_mov_b32_e32 v70, v2
	v_mov_b32_e32 v71, v2
	v_mov_b32_e32 v72, v2
	v_mov_b32_e32 v73, v2
	s_waitcnt vmcnt(0)
	v_mov_b32_e32 v82, v2
	v_mov_b32_e32 v83, v2
	v_mov_b32_e32 v84, v2
	v_mov_b32_e32 v85, v2
	v_mov_b32_e32 v86, v2
	v_mov_b32_e32 v87, v2
	v_mov_b32_e32 v88, v2
	v_mov_b32_e32 v89, v2
	v_mov_b32_e32 v98, v2
	v_mov_b32_e32 v99, v2
	v_mov_b32_e32 v100, v2
	v_mov_b32_e32 v101, v2
	v_mov_b32_e32 v102, v2
	v_mov_b32_e32 v103, v2
	v_mov_b32_e32 v104, v2
	v_mov_b32_e32 v105, v2
	v_mov_b32_e32 v114, v2
	v_mov_b32_e32 v115, v2
	v_mov_b32_e32 v116, v2
	v_mov_b32_e32 v117, v2
	v_mov_b32_e32 v118, v2
	v_mov_b32_e32 v119, v2
	v_mov_b32_e32 v120, v2
	v_mov_b32_e32 v121, v2
	v_mov_b32_e32 v74, v2
	v_mov_b32_e32 v75, v2
	v_mov_b32_e32 v76, v2
	v_mov_b32_e32 v77, v2
	v_mov_b32_e32 v78, v2
	v_mov_b32_e32 v79, v2
	v_mov_b32_e32 v80, v2
	v_mov_b32_e32 v81, v2
	v_mov_b32_e32 v90, v2
	v_mov_b32_e32 v91, v2
	v_mov_b32_e32 v92, v2
	v_mov_b32_e32 v93, v2
	v_mov_b32_e32 v94, v2
	v_mov_b32_e32 v95, v2
	v_mov_b32_e32 v96, v2
	v_mov_b32_e32 v97, v2
	v_mov_b32_e32 v106, v2
	v_mov_b32_e32 v107, v2
	v_mov_b32_e32 v108, v2
	v_mov_b32_e32 v109, v2
	v_mov_b32_e32 v110, v2
	v_mov_b32_e32 v111, v2
	v_mov_b32_e32 v112, v2
	v_mov_b32_e32 v113, v2
	v_mov_b32_e32 v122, v2
	v_mov_b32_e32 v123, v2
	v_mov_b32_e32 v124, v2
	v_mov_b32_e32 v125, v2
	v_mov_b32_e32 v126, v2
	v_mov_b32_e32 v127, v2
	v_mov_b32_e32 v128, v2
	v_mov_b32_e32 v129, v2
	.p2align	6

.LBB0_290:
	s_lshl_b32 s12, s39, 8
	s_ashr_i32 s13, s12, 31
	s_lshl_b64 s[12:13], s[12:13], 11
	s_add_u32 s12, s27, s12
	s_addc_u32 s13, s28, s13
	s_and_b64 s[14:15], s[2:3], exec
	s_cselect_b32 s42, s13, s23
	s_cselect_b32 s43, s12, s22
	s_lshl_b32 s14, s38, 8
	s_ashr_i32 s15, s14, 31
	s_lshl_b64 s[14:15], s[14:15], 11
	s_add_u32 s14, s80, s14
	s_addc_u32 s15, s81, s15
	s_and_b64 s[24:25], s[2:3], exec
	s_cselect_b32 s44, s15, s17
	s_cselect_b32 s45, s14, s16
	s_add_u32 s46, s16, 0x100
	s_addc_u32 s47, s17, 0
	s_add_u32 s16, s22, 0x40080
	v_mov_b32_e32 v2, 0
	s_addc_u32 s17, s23, 0
	s_mov_b32 s48, -2
	v_mov_b32_e32 v3, v2
	v_mov_b32_e32 v4, v2
	v_mov_b32_e32 v5, v2
	v_mov_b32_e32 v6, v2
	v_mov_b32_e32 v7, v2
	v_mov_b32_e32 v8, v2
	v_mov_b32_e32 v9, v2
	v_mov_b32_e32 v10, v2
	v_mov_b32_e32 v11, v2
	v_mov_b32_e32 v12, v2
	v_mov_b32_e32 v13, v2
	v_mov_b32_e32 v14, v2
	v_mov_b32_e32 v15, v2
	v_mov_b32_e32 v16, v2
	v_mov_b32_e32 v17, v2
	v_mov_b32_e32 v18, v2
	v_mov_b32_e32 v19, v2
	v_mov_b32_e32 v20, v2
	v_mov_b32_e32 v21, v2
	v_mov_b32_e32 v22, v2
	v_mov_b32_e32 v23, v2
	v_mov_b32_e32 v24, v2
	v_mov_b32_e32 v25, v2
	v_mov_b32_e32 v26, v2
	v_mov_b32_e32 v27, v2
	v_mov_b32_e32 v28, v2
	v_mov_b32_e32 v29, v2
	v_mov_b32_e32 v30, v2
	v_mov_b32_e32 v31, v2
	v_mov_b32_e32 v32, v2
	v_mov_b32_e32 v33, v2
	v_mov_b32_e32 v58, v2
	v_mov_b32_e32 v59, v2
	v_mov_b32_e32 v60, v2
	v_mov_b32_e32 v61, v2
	v_mov_b32_e32 v62, v2
	v_mov_b32_e32 v63, v2
	v_mov_b32_e32 v64, v2
	v_mov_b32_e32 v65, v2
	v_mov_b32_e32 v74, v2
	v_mov_b32_e32 v75, v2
	v_mov_b32_e32 v76, v2
	v_mov_b32_e32 v77, v2
	v_mov_b32_e32 v78, v2
	v_mov_b32_e32 v79, v2
	v_mov_b32_e32 v80, v2
	v_mov_b32_e32 v81, v2
	v_mov_b32_e32 v82, v2
	v_mov_b32_e32 v83, v2
	v_mov_b32_e32 v84, v2
	v_mov_b32_e32 v85, v2
	v_mov_b32_e32 v86, v2
	v_mov_b32_e32 v87, v2
	v_mov_b32_e32 v88, v2
	v_mov_b32_e32 v89, v2
	v_mov_b32_e32 v90, v2
	v_mov_b32_e32 v91, v2
	v_mov_b32_e32 v92, v2
	v_mov_b32_e32 v93, v2
	v_mov_b32_e32 v94, v2
	v_mov_b32_e32 v95, v2
	v_mov_b32_e32 v96, v2
	v_mov_b32_e32 v97, v2
	v_mov_b32_e32 v34, v2
	v_mov_b32_e32 v35, v2
	v_mov_b32_e32 v36, v2
	v_mov_b32_e32 v37, v2
	v_mov_b32_e32 v38, v2
	v_mov_b32_e32 v39, v2
	v_mov_b32_e32 v40, v2
	v_mov_b32_e32 v41, v2
	v_mov_b32_e32 v42, v2
	v_mov_b32_e32 v43, v2
	v_mov_b32_e32 v44, v2
	v_mov_b32_e32 v45, v2
	v_mov_b32_e32 v46, v2
	v_mov_b32_e32 v47, v2
	v_mov_b32_e32 v48, v2
	v_mov_b32_e32 v49, v2
	v_mov_b32_e32 v50, v2
	v_mov_b32_e32 v51, v2
	v_mov_b32_e32 v52, v2
	v_mov_b32_e32 v53, v2
	v_mov_b32_e32 v54, v2
	v_mov_b32_e32 v55, v2
	v_mov_b32_e32 v56, v2
	v_mov_b32_e32 v57, v2
	v_mov_b32_e32 v66, v2
	v_mov_b32_e32 v67, v2
	v_mov_b32_e32 v68, v2
	v_mov_b32_e32 v69, v2
	v_mov_b32_e32 v70, v2
	v_mov_b32_e32 v71, v2
	v_mov_b32_e32 v72, v2
	v_mov_b32_e32 v73, v2
	v_mov_b32_e32 v98, v2
	v_mov_b32_e32 v99, v2
	v_mov_b32_e32 v100, v2
	v_mov_b32_e32 v101, v2
	v_mov_b32_e32 v102, v2
	v_mov_b32_e32 v103, v2
	v_mov_b32_e32 v104, v2
	v_mov_b32_e32 v105, v2
	v_mov_b32_e32 v106, v2
	v_mov_b32_e32 v107, v2
	v_mov_b32_e32 v108, v2
	v_mov_b32_e32 v109, v2
	v_mov_b32_e32 v110, v2
	v_mov_b32_e32 v111, v2
	v_mov_b32_e32 v112, v2
	v_mov_b32_e32 v113, v2
	v_mov_b32_e32 v114, v2
	v_mov_b32_e32 v115, v2
	v_mov_b32_e32 v116, v2
	v_mov_b32_e32 v117, v2
	v_mov_b32_e32 v118, v2
	v_mov_b32_e32 v119, v2
	v_mov_b32_e32 v120, v2
	v_mov_b32_e32 v121, v2
	v_mov_b32_e32 v122, v2
	v_mov_b32_e32 v123, v2
	v_mov_b32_e32 v124, v2
	v_mov_b32_e32 v125, v2
	v_mov_b32_e32 v126, v2
	v_mov_b32_e32 v127, v2
	v_mov_b32_e32 v128, v2
	v_mov_b32_e32 v129, v2
	.p2align	6

.LBB0_323:
	s_add_u32 s49, s26, 0x100
	v_mov_b32_e32 v2, 0
	s_addc_u32 s50, s27, 0
	s_mov_b32 s51, -2
	v_mov_b32_e32 v3, v2
	v_mov_b32_e32 v4, v2
	v_mov_b32_e32 v5, v2
	v_mov_b32_e32 v6, v2
	v_mov_b32_e32 v7, v2
	v_mov_b32_e32 v8, v2
	v_mov_b32_e32 v9, v2
	v_mov_b32_e32 v18, v2
	v_mov_b32_e32 v19, v2
	v_mov_b32_e32 v20, v2
	v_mov_b32_e32 v21, v2
	v_mov_b32_e32 v22, v2
	v_mov_b32_e32 v23, v2
	v_mov_b32_e32 v24, v2
	v_mov_b32_e32 v25, v2
	v_mov_b32_e32 v34, v2
	v_mov_b32_e32 v35, v2
	v_mov_b32_e32 v36, v2
	v_mov_b32_e32 v37, v2
	v_mov_b32_e32 v38, v2
	v_mov_b32_e32 v39, v2
	v_mov_b32_e32 v40, v2
	v_mov_b32_e32 v41, v2
	v_mov_b32_e32 v50, v2
	v_mov_b32_e32 v51, v2
	v_mov_b32_e32 v52, v2
	v_mov_b32_e32 v53, v2
	v_mov_b32_e32 v54, v2
	v_mov_b32_e32 v55, v2
	v_mov_b32_e32 v56, v2
	v_mov_b32_e32 v57, v2
	v_mov_b32_e32 v10, v2
	v_mov_b32_e32 v11, v2
	v_mov_b32_e32 v12, v2
	v_mov_b32_e32 v13, v2
	v_mov_b32_e32 v14, v2
	v_mov_b32_e32 v15, v2
	v_mov_b32_e32 v16, v2
	v_mov_b32_e32 v17, v2
	v_mov_b32_e32 v26, v2
	v_mov_b32_e32 v27, v2
	v_mov_b32_e32 v28, v2
	v_mov_b32_e32 v29, v2
	v_mov_b32_e32 v30, v2
	v_mov_b32_e32 v31, v2
	v_mov_b32_e32 v32, v2
	v_mov_b32_e32 v33, v2
	v_mov_b32_e32 v42, v2
	v_mov_b32_e32 v43, v2
	v_mov_b32_e32 v44, v2
	v_mov_b32_e32 v45, v2
	v_mov_b32_e32 v46, v2
	v_mov_b32_e32 v47, v2
	v_mov_b32_e32 v48, v2
	v_mov_b32_e32 v49, v2
	v_mov_b32_e32 v58, v2
	v_mov_b32_e32 v59, v2
	v_mov_b32_e32 v60, v2
	v_mov_b32_e32 v61, v2
	v_mov_b32_e32 v62, v2
	v_mov_b32_e32 v63, v2
	v_mov_b32_e32 v64, v2
	v_mov_b32_e32 v65, v2
	v_mov_b32_e32 v66, v2
	v_mov_b32_e32 v67, v2
	v_mov_b32_e32 v68, v2
	v_mov_b32_e32 v69, v2
	v_mov_b32_e32 v70, v2
	v_mov_b32_e32 v71, v2
	v_mov_b32_e32 v72, v2
	v_mov_b32_e32 v73, v2
	s_waitcnt vmcnt(0)
	v_mov_b32_e32 v82, v2
	v_mov_b32_e32 v83, v2
	v_mov_b32_e32 v84, v2
	v_mov_b32_e32 v85, v2
	v_mov_b32_e32 v86, v2
	v_mov_b32_e32 v87, v2
	v_mov_b32_e32 v88, v2
	v_mov_b32_e32 v89, v2
	v_mov_b32_e32 v98, v2
	v_mov_b32_e32 v99, v2
	v_mov_b32_e32 v100, v2
	v_mov_b32_e32 v101, v2
	v_mov_b32_e32 v102, v2
	v_mov_b32_e32 v103, v2
	v_mov_b32_e32 v104, v2
	v_mov_b32_e32 v105, v2
	v_mov_b32_e32 v114, v2
	v_mov_b32_e32 v115, v2
	v_mov_b32_e32 v116, v2
	v_mov_b32_e32 v117, v2
	v_mov_b32_e32 v118, v2
	v_mov_b32_e32 v119, v2
	v_mov_b32_e32 v120, v2
	v_mov_b32_e32 v121, v2
	v_mov_b32_e32 v74, v2
	v_mov_b32_e32 v75, v2
	v_mov_b32_e32 v76, v2
	v_mov_b32_e32 v77, v2
	v_mov_b32_e32 v78, v2
	v_mov_b32_e32 v79, v2
	v_mov_b32_e32 v80, v2
	v_mov_b32_e32 v81, v2
	v_mov_b32_e32 v90, v2
	v_mov_b32_e32 v91, v2
	v_mov_b32_e32 v92, v2
	v_mov_b32_e32 v93, v2
	v_mov_b32_e32 v94, v2
	v_mov_b32_e32 v95, v2
	v_mov_b32_e32 v96, v2
	v_mov_b32_e32 v97, v2
	v_mov_b32_e32 v106, v2
	v_mov_b32_e32 v107, v2
	v_mov_b32_e32 v108, v2
	v_mov_b32_e32 v109, v2
	v_mov_b32_e32 v110, v2
	v_mov_b32_e32 v111, v2
	v_mov_b32_e32 v112, v2
	v_mov_b32_e32 v113, v2
	v_mov_b32_e32 v122, v2
	v_mov_b32_e32 v123, v2
	v_mov_b32_e32 v124, v2
	v_mov_b32_e32 v125, v2
	v_mov_b32_e32 v126, v2
	v_mov_b32_e32 v127, v2
	v_mov_b32_e32 v128, v2
	v_mov_b32_e32 v129, v2
	.p2align	6

.LBB0_360:
	s_lshl_b32 s10, s35, 8
	s_ashr_i32 s11, s10, 31
	s_lshl_b64 s[10:11], s[10:11], 11
	s_add_u32 s10, s80, s10
	s_addc_u32 s11, s81, s11
	s_and_b64 s[12:13], s[2:3], exec
	s_cselect_b32 s38, s11, s17
	s_cselect_b32 s39, s10, s16
	s_lshl_b32 s12, s34, 8
	s_ashr_i32 s13, s12, 31
	s_lshl_b64 s[12:13], s[12:13], 11
	s_add_u32 s12, s22, s12
	s_addc_u32 s13, s23, s13
	s_and_b64 s[20:21], s[2:3], exec
	s_cselect_b32 s40, s13, s15
	s_cselect_b32 s41, s12, s14
	s_add_u32 s42, s14, 0x100
	s_addc_u32 s43, s15, 0
	s_add_u32 s14, s16, 0x40080
	v_mov_b32_e32 v2, 0
	s_addc_u32 s15, s17, 0
	s_mov_b32 s44, -2
	v_mov_b32_e32 v3, v2
	v_mov_b32_e32 v4, v2
	v_mov_b32_e32 v5, v2
	v_mov_b32_e32 v6, v2
	v_mov_b32_e32 v7, v2
	v_mov_b32_e32 v8, v2
	v_mov_b32_e32 v9, v2
	v_mov_b32_e32 v18, v2
	v_mov_b32_e32 v19, v2
	v_mov_b32_e32 v20, v2
	v_mov_b32_e32 v21, v2
	v_mov_b32_e32 v22, v2
	v_mov_b32_e32 v23, v2
	v_mov_b32_e32 v24, v2
	v_mov_b32_e32 v25, v2
	v_mov_b32_e32 v34, v2
	v_mov_b32_e32 v35, v2
	v_mov_b32_e32 v36, v2
	v_mov_b32_e32 v37, v2
	v_mov_b32_e32 v38, v2
	v_mov_b32_e32 v39, v2
	v_mov_b32_e32 v40, v2
	v_mov_b32_e32 v41, v2
	v_mov_b32_e32 v50, v2
	v_mov_b32_e32 v51, v2
	v_mov_b32_e32 v52, v2
	v_mov_b32_e32 v53, v2
	v_mov_b32_e32 v54, v2
	v_mov_b32_e32 v55, v2
	v_mov_b32_e32 v56, v2
	v_mov_b32_e32 v57, v2
	v_mov_b32_e32 v10, v2
	v_mov_b32_e32 v11, v2
	v_mov_b32_e32 v12, v2
	v_mov_b32_e32 v13, v2
	v_mov_b32_e32 v14, v2
	v_mov_b32_e32 v15, v2
	v_mov_b32_e32 v16, v2
	v_mov_b32_e32 v17, v2
	v_mov_b32_e32 v26, v2
	v_mov_b32_e32 v27, v2
	v_mov_b32_e32 v28, v2
	v_mov_b32_e32 v29, v2
	v_mov_b32_e32 v30, v2
	v_mov_b32_e32 v31, v2
	v_mov_b32_e32 v32, v2
	v_mov_b32_e32 v33, v2
	v_mov_b32_e32 v42, v2
	v_mov_b32_e32 v43, v2
	v_mov_b32_e32 v44, v2
	v_mov_b32_e32 v45, v2
	v_mov_b32_e32 v46, v2
	v_mov_b32_e32 v47, v2
	v_mov_b32_e32 v48, v2
	v_mov_b32_e32 v49, v2
	v_mov_b32_e32 v58, v2
	v_mov_b32_e32 v59, v2
	v_mov_b32_e32 v60, v2
	v_mov_b32_e32 v61, v2
	v_mov_b32_e32 v62, v2
	v_mov_b32_e32 v63, v2
	v_mov_b32_e32 v64, v2
	v_mov_b32_e32 v65, v2
	v_mov_b32_e32 v66, v2
	v_mov_b32_e32 v67, v2
	v_mov_b32_e32 v68, v2
	v_mov_b32_e32 v69, v2
	v_mov_b32_e32 v70, v2
	v_mov_b32_e32 v71, v2
	v_mov_b32_e32 v72, v2
	v_mov_b32_e32 v73, v2
	s_waitcnt vmcnt(0)
	v_mov_b32_e32 v82, v2
	v_mov_b32_e32 v83, v2
	v_mov_b32_e32 v84, v2
	v_mov_b32_e32 v85, v2
	v_mov_b32_e32 v86, v2
	v_mov_b32_e32 v87, v2
	v_mov_b32_e32 v88, v2
	v_mov_b32_e32 v89, v2
	v_mov_b32_e32 v98, v2
	v_mov_b32_e32 v99, v2
	v_mov_b32_e32 v100, v2
	v_mov_b32_e32 v101, v2
	v_mov_b32_e32 v102, v2
	v_mov_b32_e32 v103, v2
	v_mov_b32_e32 v104, v2
	v_mov_b32_e32 v105, v2
	v_mov_b32_e32 v114, v2
	v_mov_b32_e32 v115, v2
	v_mov_b32_e32 v116, v2
	v_mov_b32_e32 v117, v2
	v_mov_b32_e32 v118, v2
	v_mov_b32_e32 v119, v2
	v_mov_b32_e32 v120, v2
	v_mov_b32_e32 v121, v2
	v_mov_b32_e32 v74, v2
	v_mov_b32_e32 v75, v2
	v_mov_b32_e32 v76, v2
	v_mov_b32_e32 v77, v2
	v_mov_b32_e32 v78, v2
	v_mov_b32_e32 v79, v2
	v_mov_b32_e32 v80, v2
	v_mov_b32_e32 v81, v2
	v_mov_b32_e32 v90, v2
	v_mov_b32_e32 v91, v2
	v_mov_b32_e32 v92, v2
	v_mov_b32_e32 v93, v2
	v_mov_b32_e32 v94, v2
	v_mov_b32_e32 v95, v2
	v_mov_b32_e32 v96, v2
	v_mov_b32_e32 v97, v2
	v_mov_b32_e32 v106, v2
	v_mov_b32_e32 v107, v2
	v_mov_b32_e32 v108, v2
	v_mov_b32_e32 v109, v2
	v_mov_b32_e32 v110, v2
	v_mov_b32_e32 v111, v2
	v_mov_b32_e32 v112, v2
	v_mov_b32_e32 v113, v2
	v_mov_b32_e32 v122, v2
	v_mov_b32_e32 v123, v2
	v_mov_b32_e32 v124, v2
	v_mov_b32_e32 v125, v2
	v_mov_b32_e32 v126, v2
	v_mov_b32_e32 v127, v2
	v_mov_b32_e32 v128, v2
	v_mov_b32_e32 v129, v2
	.p2align	6

.LBB0_391:
	s_lshl_b32 s20, s42, 8
	s_ashr_i32 s21, s20, 31
	s_lshl_b64 s[20:21], s[20:21], 11
	s_add_u32 s20, s18, s20
	s_addc_u32 s21, s19, s21
	s_and_b64 s[22:23], s[4:5], exec
	s_cselect_b32 s45, s21, s25
	s_cselect_b32 s46, s20, s24
	s_lshl_b32 s22, s41, 8
	s_ashr_i32 s23, s22, 31
	s_lshl_b64 s[22:23], s[22:23], 11
	s_add_u32 s22, s29, s22
	s_addc_u32 s23, s30, s23
	s_and_b64 s[26:27], s[4:5], exec
	s_cselect_b32 s47, s23, s7
	s_cselect_b32 s48, s22, s6
	s_add_u32 s49, s6, 0x100
	s_addc_u32 s50, s7, 0
	s_add_u32 s6, s24, 0x40080
	v_mov_b32_e32 v2, 0
	s_addc_u32 s7, s25, 0
	s_mov_b32 s51, -2
	v_mov_b32_e32 v3, v2
	v_mov_b32_e32 v4, v2
	v_mov_b32_e32 v5, v2
	v_mov_b32_e32 v6, v2
	v_mov_b32_e32 v7, v2
	v_mov_b32_e32 v8, v2
	v_mov_b32_e32 v9, v2
	v_mov_b32_e32 v18, v2
	v_mov_b32_e32 v19, v2
	v_mov_b32_e32 v20, v2
	v_mov_b32_e32 v21, v2
	v_mov_b32_e32 v22, v2
	v_mov_b32_e32 v23, v2
	v_mov_b32_e32 v24, v2
	v_mov_b32_e32 v25, v2
	v_mov_b32_e32 v34, v2
	v_mov_b32_e32 v35, v2
	v_mov_b32_e32 v36, v2
	v_mov_b32_e32 v37, v2
	v_mov_b32_e32 v38, v2
	v_mov_b32_e32 v39, v2
	v_mov_b32_e32 v40, v2
	v_mov_b32_e32 v41, v2
	v_mov_b32_e32 v50, v2
	v_mov_b32_e32 v51, v2
	v_mov_b32_e32 v52, v2
	v_mov_b32_e32 v53, v2
	v_mov_b32_e32 v54, v2
	v_mov_b32_e32 v55, v2
	v_mov_b32_e32 v56, v2
	v_mov_b32_e32 v57, v2
	v_mov_b32_e32 v10, v2
	v_mov_b32_e32 v11, v2
	v_mov_b32_e32 v12, v2
	v_mov_b32_e32 v13, v2
	v_mov_b32_e32 v14, v2
	v_mov_b32_e32 v15, v2
	v_mov_b32_e32 v16, v2
	v_mov_b32_e32 v17, v2
	v_mov_b32_e32 v26, v2
	v_mov_b32_e32 v27, v2
	v_mov_b32_e32 v28, v2
	v_mov_b32_e32 v29, v2
	v_mov_b32_e32 v30, v2
	v_mov_b32_e32 v31, v2
	v_mov_b32_e32 v32, v2
	v_mov_b32_e32 v33, v2
	v_mov_b32_e32 v42, v2
	v_mov_b32_e32 v43, v2
	v_mov_b32_e32 v44, v2
	v_mov_b32_e32 v45, v2
	v_mov_b32_e32 v46, v2
	v_mov_b32_e32 v47, v2
	v_mov_b32_e32 v48, v2
	v_mov_b32_e32 v49, v2
	v_mov_b32_e32 v58, v2
	v_mov_b32_e32 v59, v2
	v_mov_b32_e32 v60, v2
	v_mov_b32_e32 v61, v2
	v_mov_b32_e32 v62, v2
	v_mov_b32_e32 v63, v2
	v_mov_b32_e32 v64, v2
	v_mov_b32_e32 v65, v2
	v_mov_b32_e32 v66, v2
	v_mov_b32_e32 v67, v2
	v_mov_b32_e32 v68, v2
	v_mov_b32_e32 v69, v2
	v_mov_b32_e32 v70, v2
	v_mov_b32_e32 v71, v2
	v_mov_b32_e32 v72, v2
	v_mov_b32_e32 v73, v2
	s_waitcnt vmcnt(0)
	v_mov_b32_e32 v82, v2
	v_mov_b32_e32 v83, v2
	v_mov_b32_e32 v84, v2
	v_mov_b32_e32 v85, v2
	v_mov_b32_e32 v86, v2
	v_mov_b32_e32 v87, v2
	v_mov_b32_e32 v88, v2
	v_mov_b32_e32 v89, v2
	v_mov_b32_e32 v98, v2
	v_mov_b32_e32 v99, v2
	v_mov_b32_e32 v100, v2
	v_mov_b32_e32 v101, v2
	v_mov_b32_e32 v102, v2
	v_mov_b32_e32 v103, v2
	v_mov_b32_e32 v104, v2
	v_mov_b32_e32 v105, v2
	v_mov_b32_e32 v114, v2
	v_mov_b32_e32 v115, v2
	v_mov_b32_e32 v116, v2
	v_mov_b32_e32 v117, v2
	v_mov_b32_e32 v118, v2
	v_mov_b32_e32 v119, v2
	v_mov_b32_e32 v120, v2
	v_mov_b32_e32 v121, v2
	v_mov_b32_e32 v74, v2
	v_mov_b32_e32 v75, v2
	v_mov_b32_e32 v76, v2
	v_mov_b32_e32 v77, v2
	v_mov_b32_e32 v78, v2
	v_mov_b32_e32 v79, v2
	v_mov_b32_e32 v80, v2
	v_mov_b32_e32 v81, v2
	v_mov_b32_e32 v90, v2
	v_mov_b32_e32 v91, v2
	v_mov_b32_e32 v92, v2
	v_mov_b32_e32 v93, v2
	v_mov_b32_e32 v94, v2
	v_mov_b32_e32 v95, v2
	v_mov_b32_e32 v96, v2
	v_mov_b32_e32 v97, v2
	v_mov_b32_e32 v106, v2
	v_mov_b32_e32 v107, v2
	v_mov_b32_e32 v108, v2
	v_mov_b32_e32 v109, v2
	v_mov_b32_e32 v110, v2
	v_mov_b32_e32 v111, v2
	v_mov_b32_e32 v112, v2
	v_mov_b32_e32 v113, v2
	v_mov_b32_e32 v122, v2
	v_mov_b32_e32 v123, v2
	v_mov_b32_e32 v124, v2
	v_mov_b32_e32 v125, v2
	v_mov_b32_e32 v126, v2
	v_mov_b32_e32 v127, v2
	v_mov_b32_e32 v128, v2
	v_mov_b32_e32 v129, v2
	.p2align	6

.LBB0_438:
	s_or_b64 exec, exec, s[68:69]
	s_add_i32 s95, s95, 1
	s_add_i32 s84, s84, 0x10000
	s_cmp_eq_u32 s95, 8
	s_cbranch_scc1 .LBB0_432
	.p2align	6

.LBB0_511:
	s_lshl_b32 s22, s50, 8
	s_ashr_i32 s23, s22, 31
	s_lshl_b64 s[22:23], s[22:23], 11
	s_add_u32 s22, s31, s22
	s_addc_u32 s23, s34, s23
	s_and_b64 s[6:7], s[6:7], exec
	s_cselect_b32 s53, s23, s27
	s_cselect_b32 s54, s22, s26
	s_add_u32 s55, s26, 0x100
	s_addc_u32 s56, s27, 0
	s_add_u32 s6, s24, 0x80
	s_addc_u32 s7, s25, 0
	v_mov_b32_e32 v2, 0
	v_lshl_add_u64 v[38:39], s[6:7], 0, v[172:173]
	v_lshl_add_u64 v[40:41], s[6:7], 0, v[174:175]
	s_mov_b32 s57, -2
	s_mov_b64 s[6:7], 0
	v_mov_b32_e32 v3, v2
	v_mov_b32_e32 v4, v2
	v_mov_b32_e32 v5, v2
	v_mov_b32_e32 v6, v2
	v_mov_b32_e32 v7, v2
	v_mov_b32_e32 v8, v2
	v_mov_b32_e32 v9, v2
	v_mov_b32_e32 v18, v2
	v_mov_b32_e32 v19, v2
	v_mov_b32_e32 v20, v2
	v_mov_b32_e32 v21, v2
	v_mov_b32_e32 v22, v2
	v_mov_b32_e32 v23, v2
	s_waitcnt lgkmcnt(0)
	v_mov_b32_e32 v24, v2
	v_mov_b32_e32 v25, v2
	v_mov_b32_e32 v34, v2
	v_mov_b32_e32 v35, v2
	v_mov_b32_e32 v36, v2
	v_mov_b32_e32 v37, v2
	v_mov_b32_e32 v46, v2
	v_mov_b32_e32 v47, v2
	v_mov_b32_e32 v48, v2
	v_mov_b32_e32 v49, v2
	v_mov_b32_e32 v74, v2
	v_mov_b32_e32 v75, v2
	v_mov_b32_e32 v76, v2
	v_mov_b32_e32 v77, v2
	s_waitcnt vmcnt(0)
	v_mov_b32_e32 v86, v2
	v_mov_b32_e32 v87, v2
	v_mov_b32_e32 v88, v2
	v_mov_b32_e32 v89, v2
	v_mov_b32_e32 v10, v2
	v_mov_b32_e32 v11, v2
	v_mov_b32_e32 v12, v2
	v_mov_b32_e32 v13, v2
	v_mov_b32_e32 v14, v2
	v_mov_b32_e32 v15, v2
	v_mov_b32_e32 v16, v2
	v_mov_b32_e32 v17, v2
	v_mov_b32_e32 v26, v2
	v_mov_b32_e32 v27, v2
	v_mov_b32_e32 v28, v2
	v_mov_b32_e32 v29, v2
	v_mov_b32_e32 v30, v2
	v_mov_b32_e32 v31, v2
	v_mov_b32_e32 v32, v2
	v_mov_b32_e32 v33, v2
	v_mov_b32_e32 v58, v2
	v_mov_b32_e32 v59, v2
	v_mov_b32_e32 v60, v2
	v_mov_b32_e32 v61, v2
	v_mov_b32_e32 v62, v2
	v_mov_b32_e32 v63, v2
	v_mov_b32_e32 v64, v2
	v_mov_b32_e32 v65, v2
	v_mov_b32_e32 v90, v2
	v_mov_b32_e32 v91, v2
	v_mov_b32_e32 v92, v2
	v_mov_b32_e32 v93, v2
	v_mov_b32_e32 v94, v2
	v_mov_b32_e32 v95, v2
	v_mov_b32_e32 v96, v2
	v_mov_b32_e32 v97, v2
	v_mov_b32_e32 v98, v2
	v_mov_b32_e32 v99, v2
	v_mov_b32_e32 v100, v2
	v_mov_b32_e32 v101, v2
	v_mov_b32_e32 v102, v2
	v_mov_b32_e32 v103, v2
	v_mov_b32_e32 v104, v2
	v_mov_b32_e32 v105, v2
	v_mov_b32_e32 v114, v2
	v_mov_b32_e32 v115, v2
	v_mov_b32_e32 v116, v2
	v_mov_b32_e32 v117, v2
	v_mov_b32_e32 v118, v2
	v_mov_b32_e32 v119, v2
	v_mov_b32_e32 v120, v2
	v_mov_b32_e32 v121, v2
	v_mov_b32_e32 v130, v2
	v_mov_b32_e32 v131, v2
	v_mov_b32_e32 v132, v2
	v_mov_b32_e32 v133, v2
	v_mov_b32_e32 v134, v2
	v_mov_b32_e32 v135, v2
	v_mov_b32_e32 v136, v2
	v_mov_b32_e32 v137, v2
	v_mov_b32_e32 v146, v2
	v_mov_b32_e32 v147, v2
	v_mov_b32_e32 v148, v2
	v_mov_b32_e32 v149, v2
	v_mov_b32_e32 v150, v2
	v_mov_b32_e32 v151, v2
	v_mov_b32_e32 v152, v2
	v_mov_b32_e32 v153, v2
	v_mov_b32_e32 v106, v2
	v_mov_b32_e32 v107, v2
	v_mov_b32_e32 v108, v2
	v_mov_b32_e32 v109, v2
	v_mov_b32_e32 v110, v2
	v_mov_b32_e32 v111, v2
	v_mov_b32_e32 v112, v2
	v_mov_b32_e32 v113, v2
	v_mov_b32_e32 v122, v2
	v_mov_b32_e32 v123, v2
	v_mov_b32_e32 v124, v2
	v_mov_b32_e32 v125, v2
	v_mov_b32_e32 v126, v2
	v_mov_b32_e32 v127, v2
	v_mov_b32_e32 v128, v2
	v_mov_b32_e32 v129, v2
	v_mov_b32_e32 v138, v2
	v_mov_b32_e32 v139, v2
	v_mov_b32_e32 v140, v2
	v_mov_b32_e32 v141, v2
	v_mov_b32_e32 v142, v2
	v_mov_b32_e32 v143, v2
	v_mov_b32_e32 v144, v2
	v_mov_b32_e32 v145, v2
	v_mov_b32_e32 v154, v2
	v_mov_b32_e32 v155, v2
	v_mov_b32_e32 v156, v2
	v_mov_b32_e32 v157, v2
	v_mov_b32_e32 v158, v2
	v_mov_b32_e32 v159, v2
	v_mov_b32_e32 v160, v2
	v_mov_b32_e32 v161, v2
	.p2align	6

.LBB0_673:
	s_lshl_b32 s16, s38, 8
	s_ashr_i32 s17, s16, 31
	s_lshl_b64 s[16:17], s[16:17], 11
	s_add_u32 s16, s23, s16
	s_addc_u32 s17, s24, s17
	s_and_b64 s[4:5], s[4:5], exec
	s_cselect_b32 s41, s17, s21
	s_cselect_b32 s42, s16, s20
	s_add_u32 s43, s18, 0x100
	s_addc_u32 s44, s19, 0
	s_add_u32 s4, s20, 0x40080
	v_mov_b32_e32 v2, 0
	s_addc_u32 s5, s21, 0
	s_mov_b32 s20, -2
	v_mov_b32_e32 v3, v2
	v_mov_b32_e32 v4, v2
	v_mov_b32_e32 v5, v2
	v_mov_b32_e32 v6, v2
	v_mov_b32_e32 v7, v2
	v_mov_b32_e32 v8, v2
	v_mov_b32_e32 v9, v2
	v_mov_b32_e32 v10, v2
	v_mov_b32_e32 v11, v2
	v_mov_b32_e32 v12, v2
	v_mov_b32_e32 v13, v2
	v_mov_b32_e32 v14, v2
	v_mov_b32_e32 v15, v2
	v_mov_b32_e32 v16, v2
	v_mov_b32_e32 v17, v2
	v_mov_b32_e32 v18, v2
	v_mov_b32_e32 v19, v2
	v_mov_b32_e32 v20, v2
	v_mov_b32_e32 v21, v2
	v_mov_b32_e32 v22, v2
	v_mov_b32_e32 v23, v2
	v_mov_b32_e32 v24, v2
	v_mov_b32_e32 v25, v2
	v_mov_b32_e32 v26, v2
	v_mov_b32_e32 v27, v2
	v_mov_b32_e32 v28, v2
	v_mov_b32_e32 v29, v2
	v_mov_b32_e32 v30, v2
	v_mov_b32_e32 v31, v2
	v_mov_b32_e32 v32, v2
	v_mov_b32_e32 v33, v2
	v_mov_b32_e32 v58, v2
	v_mov_b32_e32 v59, v2
	v_mov_b32_e32 v60, v2
	v_mov_b32_e32 v61, v2
	v_mov_b32_e32 v62, v2
	v_mov_b32_e32 v63, v2
	v_mov_b32_e32 v64, v2
	v_mov_b32_e32 v65, v2
	v_mov_b32_e32 v70, v2
	v_mov_b32_e32 v71, v2
	v_mov_b32_e32 v72, v2
	v_mov_b32_e32 v73, v2
	v_mov_b32_e32 v78, v2
	v_mov_b32_e32 v79, v2
	v_mov_b32_e32 v80, v2
	v_mov_b32_e32 v81, v2
	v_mov_b32_e32 v82, v2
	v_mov_b32_e32 v83, v2
	v_mov_b32_e32 v84, v2
	v_mov_b32_e32 v85, v2
	v_mov_b32_e32 v86, v2
	v_mov_b32_e32 v87, v2
	v_mov_b32_e32 v88, v2
	v_mov_b32_e32 v89, v2
	v_mov_b32_e32 v90, v2
	v_mov_b32_e32 v91, v2
	v_mov_b32_e32 v92, v2
	v_mov_b32_e32 v93, v2
	v_mov_b32_e32 v94, v2
	v_mov_b32_e32 v95, v2
	v_mov_b32_e32 v96, v2
	v_mov_b32_e32 v97, v2
	v_mov_b32_e32 v34, v2
	v_mov_b32_e32 v35, v2
	v_mov_b32_e32 v36, v2
	v_mov_b32_e32 v37, v2
	v_mov_b32_e32 v38, v2
	v_mov_b32_e32 v39, v2
	v_mov_b32_e32 v40, v2
	v_mov_b32_e32 v41, v2
	v_mov_b32_e32 v42, v2
	v_mov_b32_e32 v43, v2
	v_mov_b32_e32 v44, v2
	v_mov_b32_e32 v45, v2
	v_mov_b32_e32 v46, v2
	v_mov_b32_e32 v47, v2
	v_mov_b32_e32 v48, v2
	v_mov_b32_e32 v49, v2
	v_mov_b32_e32 v50, v2
	v_mov_b32_e32 v51, v2
	v_mov_b32_e32 v52, v2
	v_mov_b32_e32 v53, v2
	v_mov_b32_e32 v54, v2
	v_mov_b32_e32 v55, v2
	v_mov_b32_e32 v56, v2
	v_mov_b32_e32 v57, v2
	v_mov_b32_e32 v66, v2
	v_mov_b32_e32 v67, v2
	v_mov_b32_e32 v68, v2
	v_mov_b32_e32 v69, v2
	v_mov_b32_e32 v74, v2
	v_mov_b32_e32 v75, v2
	v_mov_b32_e32 v76, v2
	v_mov_b32_e32 v77, v2
	v_mov_b32_e32 v98, v2
	v_mov_b32_e32 v99, v2
	v_mov_b32_e32 v100, v2
	v_mov_b32_e32 v101, v2
	v_mov_b32_e32 v102, v2
	v_mov_b32_e32 v103, v2
	v_mov_b32_e32 v104, v2
	v_mov_b32_e32 v105, v2
	v_mov_b32_e32 v106, v2
	v_mov_b32_e32 v107, v2
	v_mov_b32_e32 v108, v2
	v_mov_b32_e32 v109, v2
	v_mov_b32_e32 v110, v2
	v_mov_b32_e32 v111, v2
	v_mov_b32_e32 v112, v2
	v_mov_b32_e32 v113, v2
	v_mov_b32_e32 v114, v2
	v_mov_b32_e32 v115, v2
	v_mov_b32_e32 v116, v2
	v_mov_b32_e32 v117, v2
	v_mov_b32_e32 v118, v2
	v_mov_b32_e32 v119, v2
	v_mov_b32_e32 v120, v2
	v_mov_b32_e32 v121, v2
	v_mov_b32_e32 v126, v2
	v_mov_b32_e32 v127, v2
	v_mov_b32_e32 v128, v2
	v_mov_b32_e32 v129, v2
	v_mov_b32_e32 v130, v2
	v_mov_b32_e32 v131, v2
	v_mov_b32_e32 v132, v2
	v_mov_b32_e32 v133, v2
	.p2align	6
